# code placement scan: attention code +8 bytes (same 8-byte phase), GEMM placement unchanged
# baseline (speedup 1.0000x reference)
; #define ATT_WAIT_BAR() asm volatile("s_waitcnt vmcnt(0) lgkmcnt(0)\n\ts_barrier" ::: "memory")
; DI void attn_phase(const Params& P, char* shm) {
;     ...
;     for (unsigned k = 0; k < 8; ++k) {
;         const unsigned q = (xcd + k) & 7u; unsigned* cnt = P.counter + 16 * q;
;         for (;;) {
;             if (tid == 0) su[0] = atomicAdd(cnt, 1u);
;             ATT_WAIT_BAR();
;             const unsigned ui = su[0];
;             ATT_WAIT_BAR();
;             if (ui >= 384u) break;
;             const unsigned e = P.order[q * 384 + ui]; const int kind = e >> 28, b = (e >> 24) & 15, h = (e >> 16) & 255, qb = e & 0xffff;
.LBB0_316:
	s_nop 0
	s_nop 0
	v_writelane_b32 v255, 0, 61
	s_nop 0
	s_mov_b32 s0, 0x40000000
	v_writelane_b32 v255, s0, 62
	s_nop 0
	v_readlane_b32 s0, v255, 29
	s_add_i32 s0, s1, s0
	v_writelane_b32 v255, s1, 45
	s_and_b32 s0, s0, 7
	s_lshl_b32 s1, s0, 6
	v_readlane_b32 s2, v255, 25
	s_add_u32 s42, s2, s1
	v_readlane_b32 s1, v255, 26
	s_mul_i32 s41, s0, 0x180
	s_addc_u32 s43, s1, 0
	v_writelane_b32 v255, s41, 46
	v_writelane_b32 v255, s42, 47
	s_nop 1
	v_writelane_b32 v255, s43, 48
	s_branch .LBB0_320

; DI void attn_phase(const Params& P, char* shm) {
;     ...
;     __builtin_amdgcn_s_setprio(0);
.LBB0_438:
	s_nop 0
	s_nop 0
	s_nop 0
	s_nop 0
	s_nop 0
	s_nop 0
	s_nop 0
	s_nop 0
	s_nop 0
	s_nop 0
	s_nop 0
	s_nop 0
	s_nop 0
	s_nop 0
	s_nop 0
	s_setprio 0
	s_mov_b64 s[0:1], 0
